# retention output: group-norm epilogue with the four row groups' cross-lane reductions interleaved (8 round trips instead of 32 serial)
# baseline (speedup 1.0000x reference)
.LBB0_802:
	s_and_b32 s12, s11, 3
	v_cvt_f32_ubyte0_e32 v0, s12
	v_sub_f32_e32 v0, 0xc0a00000, v0
	v_cmp_gt_f32_e32 vcc, s20, v0
	s_ashr_i32 s8, s11, 6
	s_ashr_i32 s9, s8, 31
	v_cndmask_b32_e32 v1, 0, v228, vcc
	v_add_f32_e32 v0, v0, v1
	s_lshl_b64 s[0:1], s[8:9], 11
	s_and_b32 s13, s10, 0x780
	v_exp_f32_e32 v0, v0
	s_or_b32 s0, s0, s13
	s_and_b64 s[14:15], vcc, exec
	s_cselect_b32 s9, 0xffffffc0, 0
	v_ldexp_f32 v16, v0, s9
	v_sub_f32_e32 v2, 1.0, v16
	v_add_f32_e32 v0, -1.0, v2
	v_sub_f32_e32 v1, v0, v2
	v_add_f32_e32 v1, 1.0, v1
	v_sub_f32_e64 v0, -v16, v0
	v_add_f32_e32 v3, v0, v1
	v_frexp_mant_f32_e32 v0, v2
	v_cmp_gt_f32_e32 vcc, s17, v0
	v_cvt_f64_f32_e32 v[0:1], v2
	v_frexp_exp_i32_f64_e32 v0, v[0:1]
	v_subbrev_co_u32_e32 v8, vcc, 0, v0, vcc
	v_sub_u32_e32 v0, 0, v8
	v_ldexp_f32 v1, v2, v0
	v_add_f32_e32 v2, -1.0, v1
	v_add_f32_e32 v4, 1.0, v1
	v_ldexp_f32 v0, v3, v0
	v_add_f32_e32 v3, 1.0, v2
	v_add_f32_e32 v5, -1.0, v4
	v_sub_f32_e32 v3, v1, v3
	v_sub_f32_e32 v1, v1, v5
	v_add_f32_e32 v3, v0, v3
	v_add_f32_e32 v0, v0, v1
	v_add_f32_e32 v9, v4, v0
	v_rcp_f32_e32 v11, v9
	v_sub_f32_e32 v1, v9, v4
	v_sub_f32_e32 v10, v0, v1
	v_add_f32_e32 v1, v2, v3
	v_mul_f32_e32 v13, v1, v11
	v_sub_f32_e32 v0, v1, v2
	v_mul_f32_e32 v2, v9, v13
	v_fma_f32 v4, v13, v9, -v2
	v_fmac_f32_e32 v4, v13, v10
	v_sub_f32_e32 v12, v3, v0
	v_add_f32_e32 v0, v2, v4
	v_sub_f32_e32 v3, v1, v0
	v_pk_add_f32 v[6:7], v[0:1], v[2:3] neg_lo:[0,1] neg_hi:[0,1]
	v_mov_b32_e32 v5, v0
	v_pk_add_f32 v[0:1], v[6:7], v[4:5] neg_lo:[0,1] neg_hi:[0,1]
	v_cmp_nlt_f32_e32 vcc, 1.0, v16
	v_add_f32_e32 v1, v12, v1
	v_add_f32_e32 v0, v0, v1
	v_add_f32_e32 v1, v3, v0
	v_mul_f32_e32 v12, v11, v1
	v_mul_f32_e32 v2, v9, v12
	v_fma_f32 v4, v12, v9, -v2
	v_fmac_f32_e32 v4, v12, v10
	v_sub_f32_e32 v3, v3, v1
	v_add_f32_e32 v9, v0, v3
	v_add_f32_e32 v0, v2, v4
	v_sub_f32_e32 v3, v1, v0
	v_pk_add_f32 v[6:7], v[0:1], v[2:3] neg_lo:[0,1] neg_hi:[0,1]
	v_mov_b32_e32 v5, v0
	v_pk_add_f32 v[0:1], v[6:7], v[4:5] neg_lo:[0,1] neg_hi:[0,1]
	v_mov_b64_e32 v[98:99], s[6:7]
	v_add_f32_e32 v1, v9, v1
	v_add_f32_e32 v0, v0, v1
	v_add_f32_e32 v1, v13, v12
	v_add_f32_e32 v0, v3, v0
	v_sub_f32_e32 v2, v1, v13
	v_mul_f32_e32 v0, v11, v0
	v_sub_f32_e32 v2, v12, v2
	v_add_f32_e32 v2, v2, v0
	v_add_f32_e32 v4, v1, v2
	v_mul_f32_e32 v5, v4, v4
	v_fmamk_f32 v0, v5, 0x3e9b6dac, v222
	v_fmaak_f32 v185, v5, v0, 0x3f2aaada
	v_cvt_f32_i32_e32 v0, v8
	v_sub_f32_e32 v1, v4, v1
	v_sub_f32_e32 v1, v2, v1
	v_ldexp_f32 v6, v1, 1
	v_mul_f32_e32 v1, v4, v5
	v_ldexp_f32 v3, v4, 1
	v_pk_mul_f32 v[4:5], v[0:1], v[184:185]
	s_lshl_b32 s88, s12, 8
	v_fma_f32 v2, v0, s23, -v4
	v_fmac_f32_e32 v2, 0xb102e308, v0
	v_pk_add_f32 v[0:1], v[4:5], v[2:3]
	v_add_u32_e32 v185, 0, v100
	v_sub_f32_e32 v3, v1, v3
	v_sub_f32_e32 v3, v5, v3
	v_add_f32_e32 v7, v6, v3
	v_mov_b32_e32 v6, v4
	v_pk_add_f32 v[4:5], v[0:1], v[4:5] neg_lo:[0,1] neg_hi:[0,1]
	v_pk_add_f32 v[8:9], v[0:1], v[6:7]
	v_mov_b32_e32 v3, v0
	v_mov_b32_e32 v5, v9
	v_pk_add_f32 v[10:11], v[2:3], v[4:5] neg_lo:[0,1] neg_hi:[0,1]
	v_pk_add_f32 v[2:3], v[2:3], v[4:5]
	v_mov_b32_e32 v14, v1
	v_pk_add_f32 v[4:5], v[2:3], v[0:1] op_sel:[1,0] op_sel_hi:[0,1] neg_lo:[0,1] neg_hi:[0,1]
	v_pk_add_f32 v[12:13], v[8:9], v[4:5] op_sel_hi:[1,0] neg_lo:[0,1] neg_hi:[0,1]
	v_mov_b32_e32 v8, v9
	v_mov_b32_e32 v9, v3
	v_mov_b32_e32 v15, v4
	v_pk_add_f32 v[4:5], v[8:9], v[14:15] neg_lo:[0,1] neg_hi:[0,1]
	v_mov_b32_e32 v6, v7
	v_mov_b32_e32 v7, v0
	v_pk_add_f32 v[0:1], v[6:7], v[4:5] neg_lo:[0,1] neg_hi:[0,1]
	v_mov_b32_e32 v12, v10
	v_pk_add_f32 v[4:5], v[12:13], v[0:1]
	v_mov_b32_e32 v11, v3
	v_pk_add_f32 v[6:7], v[4:5], v[4:5] op_sel:[0,1] op_sel_hi:[1,0]
	s_lshl_b32 s8, s8, 2
	v_pk_add_f32 v[2:3], v[2:3], v[6:7] op_sel:[1,0] op_sel_hi:[0,1]
	v_mov_b32_e32 v5, v2
	v_pk_add_f32 v[8:9], v[4:5], v[10:11] neg_lo:[0,1] neg_hi:[0,1]
	v_mov_b32_e32 v1, v6
	v_sub_f32_e32 v3, v4, v8
	v_pk_add_f32 v[0:1], v[0:1], v[8:9] neg_lo:[0,1] neg_hi:[0,1]
	v_sub_f32_e32 v3, v10, v3
	v_add_f32_e32 v0, v0, v3
	v_add_f32_e32 v0, v0, v1
	v_add_f32_e32 v0, v2, v0
	v_cndmask_b32_e32 v0, v225, v0, vcc
	v_cmp_neq_f32_e32 vcc, 1.0, v16
	s_or_b32 s8, s8, s12
	v_add_u32_e32 v197, 0, v101
	v_cndmask_b32_e32 v0, v229, v0, vcc
	v_cmp_gt_f32_e32 vcc, s25, v16
	s_ashr_i32 s9, s8, 31
	v_add_u32_e32 v198, 0, v102
	v_cndmask_b32_e64 v200, v0, -v16, vcc
	v_lshl_add_u64 v[0:1], s[0:1], 0, v[82:83]
	v_mad_u64_u32 v[2:3], s[14:15], v0, s97, v[98:99]
	v_mad_i32_i24 v3, v1, s97, v3
	v_lshl_add_u64 v[0:1], v[2:3], 0, s[88:89]
	v_lshl_add_u64 v[0:1], v[0:1], 0, v[32:33]
	v_add_co_u32_e32 v2, vcc, s93, v0
	s_lshl_b64 s[8:9], s[8:9], 11
	s_nop 0
	v_addc_co_u32_e32 v3, vcc, 0, v1, vcc
	v_add_co_u32_e32 v0, vcc, s96, v0
	global_load_dwordx4 v[42:45], v[2:3], off offset:3072
	s_nop 0
	v_addc_co_u32_e32 v1, vcc, 0, v1, vcc
	global_load_dwordx4 v[46:49], v[0:1], off
	global_load_dwordx4 v[28:31], v[0:1], off offset:1024
	v_lshl_add_u64 v[0:1], s[0:1], 0, v[92:93]
	v_mad_u64_u32 v[2:3], s[14:15], v0, s97, v[98:99]
	v_mad_i32_i24 v3, v1, s97, v3
	v_lshl_add_u64 v[0:1], v[2:3], 0, s[88:89]
	v_lshl_add_u64 v[0:1], v[0:1], 0, v[32:33]
	v_add_co_u32_e32 v2, vcc, s93, v0
	v_add_u32_e32 v199, 0, v103
	s_nop 0
	v_addc_co_u32_e32 v3, vcc, 0, v1, vcc
	v_add_co_u32_e32 v0, vcc, s96, v0
	global_load_dwordx4 v[34:37], v[2:3], off offset:3072
	s_nop 0
	v_addc_co_u32_e32 v1, vcc, 0, v1, vcc
	global_load_dwordx4 v[38:41], v[0:1], off
	global_load_dwordx4 v[16:19], v[0:1], off offset:1024
	v_lshl_add_u64 v[0:1], s[0:1], 0, v[94:95]
	v_mad_u64_u32 v[2:3], s[14:15], v0, s97, v[98:99]
	v_mad_i32_i24 v3, v1, s97, v3
	v_lshl_add_u64 v[0:1], v[2:3], 0, s[88:89]
	v_lshl_add_u64 v[0:1], v[0:1], 0, v[32:33]
	v_add_co_u32_e32 v2, vcc, s93, v0
	s_or_b32 s8, s8, s13
	s_nop 0
	v_addc_co_u32_e32 v3, vcc, 0, v1, vcc
	v_add_co_u32_e32 v0, vcc, s96, v0
	global_load_dwordx4 v[20:23], v[2:3], off offset:3072
	s_nop 0
	v_addc_co_u32_e32 v1, vcc, 0, v1, vcc
	global_load_dwordx4 v[24:27], v[0:1], off
	global_load_dwordx4 v[4:7], v[0:1], off offset:1024
	v_lshl_add_u64 v[0:1], s[0:1], 0, v[96:97]
	v_mad_u64_u32 v[2:3], s[14:15], v0, s97, v[98:99]
	v_mad_i32_i24 v3, v1, s97, v3
	v_lshl_add_u64 v[0:1], v[2:3], 0, s[88:89]
	v_lshl_add_u64 v[0:1], v[0:1], 0, v[32:33]
	v_add_co_u32_e32 v2, vcc, s93, v0
	v_mul_f32_e32 v200, 0x3fb8aa3b, v200
	s_nop 0
	v_addc_co_u32_e32 v3, vcc, 0, v1, vcc
	v_add_co_u32_e32 v0, vcc, s96, v0
	global_load_dwordx4 v[8:11], v[2:3], off offset:3072
	s_nop 0
	v_addc_co_u32_e32 v1, vcc, 0, v1, vcc
	global_load_dwordx4 v[12:15], v[0:1], off
	s_nop 0
	global_load_dwordx4 v[0:3], v[0:1], off offset:1024
	s_barrier
	s_waitcnt vmcnt(11)
	ds_write_b128 v185, v[42:45]
	s_waitcnt vmcnt(10)
	ds_write_b128 v185, v[46:49] offset:34816
	v_add_u32_e32 v42, s22, v100
	s_waitcnt vmcnt(9)
	ds_write_b128 v42, v[28:31]
	v_add_u32_e32 v28, s22, v101
	s_waitcnt vmcnt(8)
	ds_write_b128 v197, v[34:37]
	s_waitcnt vmcnt(7)
	ds_write_b128 v197, v[38:41] offset:34816
	s_waitcnt vmcnt(6)
	ds_write_b128 v28, v[16:19]
	v_add_u32_e32 v16, s22, v102
	s_waitcnt vmcnt(5)
	ds_write_b128 v198, v[20:23]
	s_waitcnt vmcnt(4)
	ds_write_b128 v198, v[24:27] offset:34816
	s_waitcnt vmcnt(3)
	ds_write_b128 v16, v[4:7]
	v_add_u32_e32 v4, s22, v103
	s_waitcnt vmcnt(2)
	ds_write_b128 v199, v[8:11]
	s_waitcnt vmcnt(1)
	ds_write_b128 v199, v[12:15] offset:34816
	s_waitcnt vmcnt(0)
	ds_write_b128 v4, v[0:3]
	v_lshl_add_u64 v[0:1], s[8:9], 0, v[82:83]
	v_lshlrev_b64 v[0:1], 8, v[0:1]
	v_lshl_add_u64 v[2:3], v[84:85], 0, v[0:1]
	v_lshl_add_u64 v[0:1], v[86:87], 0, v[0:1]
	global_load_dwordx4 v[16:19], v[2:3], off
	global_load_dwordx4 v[34:37], v[0:1], off
	v_lshl_add_u64 v[0:1], s[8:9], 0, v[92:93]
	v_lshlrev_b64 v[0:1], 8, v[0:1]
	v_lshl_add_u64 v[2:3], v[84:85], 0, v[0:1]
	v_lshl_add_u64 v[0:1], v[86:87], 0, v[0:1]
	global_load_dwordx4 v[20:23], v[2:3], off
	global_load_dwordx4 v[38:41], v[0:1], off
	v_lshl_add_u64 v[0:1], s[8:9], 0, v[94:95]
	v_lshlrev_b64 v[0:1], 8, v[0:1]
	v_lshl_add_u64 v[2:3], v[84:85], 0, v[0:1]
	v_lshl_add_u64 v[0:1], v[86:87], 0, v[0:1]
	global_load_dwordx4 v[24:27], v[2:3], off
	global_load_dwordx4 v[42:45], v[0:1], off
	v_lshl_add_u64 v[0:1], s[8:9], 0, v[96:97]
	v_lshlrev_b64 v[0:1], 8, v[0:1]
	v_lshl_add_u64 v[2:3], v[84:85], 0, v[0:1]
	v_lshl_add_u64 v[0:1], v[86:87], 0, v[0:1]
	global_load_dwordx4 v[28:31], v[2:3], off
	global_load_dwordx4 v[78:81], v[0:1], off
	s_waitcnt lgkmcnt(0)
	s_barrier
	ds_read_b128 v[74:77], v173
	ds_read_b128 v[70:73], v173 offset:32
	ds_read_b128 v[66:69], v173 offset:64
	ds_read_b128 v[62:65], v173 offset:96
	ds_read_b128 v[58:61], v173 offset:128
	ds_read_b128 v[54:57], v173 offset:160
	ds_read_b128 v[50:53], v173 offset:192
	ds_read_b128 v[46:49], v173 offset:224
	ds_read_b128 v[0:3], v174 offset:34816
	ds_read_b128 v[202:205], v174 offset:34848
	s_waitcnt lgkmcnt(1)
	v_mfma_f32_32x32x16_bf16 v[0:15], v[0:3], v[74:77], 0
	v_mul_f32_e32 v201, v200, v104
	v_exp_f32_e32 v201, v201
	s_lshl_b32 s8, s12, 9
	s_mov_b32 s9, s89
	s_add_i32 s11, s11, s28
	s_add_i32 s10, s10, s16
	s_cmpk_lt_i32 s11, 0x400
	s_waitcnt lgkmcnt(0)
	v_mfma_f32_32x32x16_bf16 v[0:15], v[202:205], v[70:73], v[0:15]
	ds_read_b128 v[202:205], v174 offset:34880
	s_waitcnt lgkmcnt(0)
	v_mfma_f32_32x32x16_bf16 v[0:15], v[202:205], v[66:69], v[0:15]
	ds_read_b128 v[202:205], v174 offset:34912
	s_waitcnt lgkmcnt(0)
	v_mfma_f32_32x32x16_bf16 v[0:15], v[202:205], v[62:65], v[0:15]
	ds_read_b128 v[202:205], v174 offset:34944
	s_waitcnt lgkmcnt(0)
	v_mfma_f32_32x32x16_bf16 v[0:15], v[202:205], v[58:61], v[0:15]
	ds_read_b128 v[202:205], v174 offset:34976
	s_waitcnt lgkmcnt(0)
	v_mfma_f32_32x32x16_bf16 v[0:15], v[202:205], v[54:57], v[0:15]
	ds_read_b128 v[202:205], v174 offset:35008
	s_waitcnt lgkmcnt(0)
	v_mfma_f32_32x32x16_bf16 v[0:15], v[202:205], v[50:53], v[0:15]
	ds_read_b128 v[202:205], v174 offset:35040
	s_waitcnt lgkmcnt(0)
	v_mfma_f32_32x32x16_bf16 v[0:15], v[202:205], v[46:49], v[0:15]
	s_nop 11
	v_mul_f32_e32 v0, v0, v201
	v_mul_f32_e32 v201, v200, v105
	v_exp_f32_e32 v201, v201
	s_nop 0
	v_mul_f32_e32 v1, v1, v201
	v_mul_f32_e32 v201, v200, v106
	v_exp_f32_e32 v201, v201
	v_cvt_pk_bf16_f32 v0, v0, v1
	s_nop 0
	v_mul_f32_e32 v2, v2, v201
	v_mul_f32_e32 v201, v200, v107
	v_exp_f32_e32 v201, v201
	s_nop 0
	v_mul_f32_e32 v3, v3, v201
	v_cvt_pk_bf16_f32 v1, v2, v3
	ds_write_b64 v177, v[0:1]
	v_mul_f32_e32 v0, v200, v108
	v_mul_f32_e32 v1, v200, v109
	v_exp_f32_e32 v0, v0
	v_exp_f32_e32 v1, v1
	v_mul_f32_e32 v2, v200, v110
	v_mul_f32_e32 v3, v200, v111
	v_exp_f32_e32 v2, v2
	v_exp_f32_e32 v3, v3
	v_mul_f32_e32 v0, v4, v0
	v_mul_f32_e32 v1, v5, v1
	v_mul_f32_e32 v2, v6, v2
	v_mul_f32_e32 v3, v7, v3
	v_cvt_pk_bf16_f32 v0, v0, v1
	v_cvt_pk_bf16_f32 v1, v2, v3
	ds_write_b64 v190, v[0:1]
	v_mul_f32_e32 v0, v200, v112
	v_mul_f32_e32 v1, v200, v113
	v_exp_f32_e32 v0, v0
	v_exp_f32_e32 v1, v1
	v_mul_f32_e32 v2, v200, v114
	v_mul_f32_e32 v3, v200, v115
	v_exp_f32_e32 v2, v2
	v_exp_f32_e32 v3, v3
	v_mul_f32_e32 v0, v8, v0
	v_mul_f32_e32 v1, v9, v1
	v_mul_f32_e32 v2, v10, v2
	v_mul_f32_e32 v3, v11, v3
	v_cvt_pk_bf16_f32 v0, v0, v1
	v_cvt_pk_bf16_f32 v1, v2, v3
	ds_write_b64 v191, v[0:1]
	v_mul_f32_e32 v0, v200, v116
	v_mul_f32_e32 v1, v200, v117
	v_exp_f32_e32 v0, v0
	v_exp_f32_e32 v1, v1
	v_mul_f32_e32 v2, v200, v118
	v_mul_f32_e32 v3, v200, v119
	v_exp_f32_e32 v2, v2
	v_exp_f32_e32 v3, v3
	v_mul_f32_e32 v0, v12, v0
	v_mul_f32_e32 v1, v13, v1
	v_mul_f32_e32 v2, v14, v2
	v_mul_f32_e32 v3, v15, v3
	v_cvt_pk_bf16_f32 v0, v0, v1
	v_cvt_pk_bf16_f32 v1, v2, v3
	ds_write_b64 v192, v[0:1]
	ds_read_b128 v[0:3], v174 offset:43520
	ds_read_b128 v[202:205], v174 offset:43552
	s_waitcnt lgkmcnt(1)
	v_mfma_f32_32x32x16_bf16 v[0:15], v[0:3], v[74:77], 0
	v_mul_f32_e32 v201, v200, v120
	v_exp_f32_e32 v201, v201
	s_waitcnt lgkmcnt(0)
	v_mfma_f32_32x32x16_bf16 v[0:15], v[202:205], v[70:73], v[0:15]
	ds_read_b128 v[202:205], v174 offset:43584
	s_waitcnt lgkmcnt(0)
	v_mfma_f32_32x32x16_bf16 v[0:15], v[202:205], v[66:69], v[0:15]
	ds_read_b128 v[202:205], v174 offset:43616
	s_waitcnt lgkmcnt(0)
	v_mfma_f32_32x32x16_bf16 v[0:15], v[202:205], v[62:65], v[0:15]
	ds_read_b128 v[202:205], v174 offset:43648
	s_waitcnt lgkmcnt(0)
	v_mfma_f32_32x32x16_bf16 v[0:15], v[202:205], v[58:61], v[0:15]
	ds_read_b128 v[202:205], v174 offset:43680
	s_waitcnt lgkmcnt(0)
	v_mfma_f32_32x32x16_bf16 v[0:15], v[202:205], v[54:57], v[0:15]
	ds_read_b128 v[202:205], v174 offset:43712
	s_waitcnt lgkmcnt(0)
	v_mfma_f32_32x32x16_bf16 v[0:15], v[202:205], v[50:53], v[0:15]
	ds_read_b128 v[202:205], v174 offset:43744
	s_waitcnt lgkmcnt(0)
	v_mfma_f32_32x32x16_bf16 v[0:15], v[202:205], v[46:49], v[0:15]
	s_nop 11
	v_mul_f32_e32 v0, v201, v0
	v_mul_f32_e32 v201, v200, v121
	v_exp_f32_e32 v201, v201
	s_nop 0
	v_mul_f32_e32 v1, v201, v1
	v_mul_f32_e32 v201, v200, v122
	v_exp_f32_e32 v201, v201
	v_cvt_pk_bf16_f32 v0, v0, v1
	s_nop 0
	v_mul_f32_e32 v2, v201, v2
	v_mul_f32_e32 v201, v200, v123
	v_exp_f32_e32 v201, v201
	s_nop 0
	v_mul_f32_e32 v3, v201, v3
	v_cvt_pk_bf16_f32 v1, v2, v3
	ds_write_b64 v193, v[0:1]
	v_mul_f32_e32 v0, v200, v124
	v_mul_f32_e32 v1, v200, v125
	v_exp_f32_e32 v0, v0
	v_exp_f32_e32 v1, v1
	v_mul_f32_e32 v2, v200, v126
	v_mul_f32_e32 v3, v200, v127
	v_exp_f32_e32 v2, v2
	v_exp_f32_e32 v3, v3
	v_mul_f32_e32 v0, v0, v4
	v_mul_f32_e32 v1, v1, v5
	v_mul_f32_e32 v2, v2, v6
	v_mul_f32_e32 v3, v3, v7
	v_cvt_pk_bf16_f32 v0, v0, v1
	v_cvt_pk_bf16_f32 v1, v2, v3
	ds_write_b64 v194, v[0:1]
	v_mul_f32_e32 v0, v200, v128
	v_mul_f32_e32 v1, v200, v129
	v_exp_f32_e32 v0, v0
	v_exp_f32_e32 v1, v1
	v_mul_f32_e32 v2, v200, v130
	v_mul_f32_e32 v3, v200, v131
	v_exp_f32_e32 v2, v2
	v_exp_f32_e32 v3, v3
	v_mul_f32_e32 v0, v0, v8
	v_mul_f32_e32 v1, v1, v9
	v_mul_f32_e32 v2, v2, v10
	v_mul_f32_e32 v3, v3, v11
	v_cvt_pk_bf16_f32 v0, v0, v1
	v_cvt_pk_bf16_f32 v1, v2, v3
	ds_write_b64 v195, v[0:1]
	v_mul_f32_e32 v0, v200, v132
	v_mul_f32_e32 v1, v200, v133
	v_exp_f32_e32 v0, v0
	v_exp_f32_e32 v1, v1
	v_mul_f32_e32 v2, v200, v134
	v_mul_f32_e32 v3, v200, v135
	v_exp_f32_e32 v2, v2
	v_exp_f32_e32 v3, v3
	v_mul_f32_e32 v0, v0, v12
	v_mul_f32_e32 v1, v1, v13
	v_mul_f32_e32 v2, v2, v14
	v_mul_f32_e32 v3, v3, v15
	v_cvt_pk_bf16_f32 v0, v0, v1
	v_cvt_pk_bf16_f32 v1, v2, v3
	ds_write_b64 v196, v[0:1]
	s_waitcnt lgkmcnt(0)
	s_barrier
	s_waitcnt vmcnt(7)
	ds_write_b128 v185, v[16:19] offset:34816
	s_waitcnt vmcnt(5)
	ds_write_b128 v197, v[20:23] offset:34816
	s_waitcnt vmcnt(3)
	ds_write_b128 v198, v[24:27] offset:34816
	s_waitcnt vmcnt(1)
	ds_write_b128 v199, v[28:31] offset:34816
	s_waitcnt lgkmcnt(0)
	s_barrier
	ds_read_b128 v[0:3], v174 offset:34816
	ds_read_b128 v[16:19], v174 offset:34848
	s_waitcnt lgkmcnt(1)
	v_mfma_f32_32x32x16_bf16 v[0:15], v[74:77], v[0:3], 0
	ds_read_b128 v[202:205], v174 offset:43552
	v_mul_f32_e32 v201, v200, v136
	v_cmp_gt_f32_e32 vcc, s20, v201
	s_nop 1
	v_cndmask_b32_e32 v201, 0, v228, vcc
	v_fmac_f32_e32 v201, v200, v136
	s_waitcnt lgkmcnt(1)
	v_mfma_f32_32x32x16_bf16 v[0:15], v[70:73], v[16:19], v[0:15]
	ds_read_b128 v[16:19], v174 offset:34880
	v_exp_f32_e32 v201, v201
	s_waitcnt lgkmcnt(0)
	v_mfma_f32_32x32x16_bf16 v[0:15], v[66:69], v[16:19], v[0:15]
	ds_read_b128 v[16:19], v174 offset:34912
	s_waitcnt lgkmcnt(0)
	v_mfma_f32_32x32x16_bf16 v[0:15], v[62:65], v[16:19], v[0:15]
	ds_read_b128 v[16:19], v174 offset:34944
	s_waitcnt lgkmcnt(0)
	v_mfma_f32_32x32x16_bf16 v[0:15], v[58:61], v[16:19], v[0:15]
	ds_read_b128 v[16:19], v174 offset:34976
	s_waitcnt lgkmcnt(0)
	v_mfma_f32_32x32x16_bf16 v[0:15], v[54:57], v[16:19], v[0:15]
	ds_read_b128 v[16:19], v174 offset:35008
	s_waitcnt lgkmcnt(0)
	v_mfma_f32_32x32x16_bf16 v[0:15], v[50:53], v[16:19], v[0:15]
	ds_read_b128 v[16:19], v174 offset:35040
	s_waitcnt lgkmcnt(0)
	v_mfma_f32_32x32x16_bf16 v[0:15], v[46:49], v[16:19], v[0:15]
	ds_read_b128 v[16:19], v174 offset:43520
	s_waitcnt lgkmcnt(0)
	v_mfma_f32_32x32x16_bf16 v[16:31], v[74:77], v[16:19], 0
	v_mfma_f32_32x32x16_bf16 v[16:31], v[70:73], v[202:205], v[16:31]
	ds_read_b128 v[202:205], v174 offset:43584
	s_waitcnt lgkmcnt(0)
	v_mfma_f32_32x32x16_bf16 v[16:31], v[66:69], v[202:205], v[16:31]
	ds_read_b128 v[202:205], v174 offset:43616
	s_waitcnt lgkmcnt(0)
	v_mfma_f32_32x32x16_bf16 v[16:31], v[62:65], v[202:205], v[16:31]
	ds_read_b128 v[202:205], v174 offset:43648
	s_waitcnt lgkmcnt(0)
	v_mfma_f32_32x32x16_bf16 v[16:31], v[58:61], v[202:205], v[16:31]
	ds_read_b128 v[202:205], v174 offset:43680
	s_waitcnt lgkmcnt(0)
	v_mfma_f32_32x32x16_bf16 v[16:31], v[54:57], v[202:205], v[16:31]
	ds_read_b128 v[202:205], v174 offset:43712
	s_waitcnt lgkmcnt(0)
	v_mfma_f32_32x32x16_bf16 v[16:31], v[50:53], v[202:205], v[16:31]
	ds_read_b128 v[202:205], v174 offset:43744
	s_waitcnt lgkmcnt(0)
	s_barrier
	ds_write_b128 v185, v[34:37] offset:34816
	ds_write_b128 v197, v[38:41] offset:34816
	ds_write_b128 v198, v[42:45] offset:34816
	s_waitcnt vmcnt(0)
	ds_write_b128 v199, v[78:81] offset:34816
	s_waitcnt lgkmcnt(0)
	s_barrier
	v_mfma_f32_32x32x16_bf16 v[16:31], v[46:49], v[202:205], v[16:31]
	v_cndmask_b32_e32 v202, 0, v223, vcc
	v_ldexp_f32 v202, v201, v202
	v_mul_f32_e32 v201, v200, v137
	v_cmp_gt_f32_e32 vcc, s20, v201
	ds_read_b128 v[34:37], v174 offset:34816
	ds_read_b128 v[38:41], v174 offset:34848
	v_cndmask_b32_e32 v201, 0, v228, vcc
	v_fmac_f32_e32 v201, v200, v137
	v_exp_f32_e32 v201, v201
	v_cndmask_b32_e32 v203, 0, v223, vcc
	v_ldexp_f32 v203, v201, v203
	v_mul_f32_e32 v201, v200, v138
	v_cmp_gt_f32_e32 vcc, s20, v201
	v_pk_mul_f32 v[0:1], v[202:203], v[0:1]
	v_pk_mul_f32 v[16:17], v[202:203], v[16:17]
	v_cndmask_b32_e32 v201, 0, v228, vcc
	v_fmac_f32_e32 v201, v200, v138
	v_exp_f32_e32 v201, v201
	v_cndmask_b32_e32 v204, 0, v223, vcc
	v_ldexp_f32 v204, v201, v204
	v_mul_f32_e32 v201, v200, v139
	v_cmp_gt_f32_e32 vcc, s20, v201
	s_nop 1
	v_cndmask_b32_e32 v201, 0, v228, vcc
	v_fmac_f32_e32 v201, v200, v139
	v_exp_f32_e32 v201, v201
	v_cndmask_b32_e32 v205, 0, v223, vcc
	v_ldexp_f32 v205, v201, v205
	v_mul_f32_e32 v201, v200, v140
	v_cmp_gt_f32_e32 vcc, s20, v201
	v_pk_mul_f32 v[2:3], v[204:205], v[2:3]
	v_pk_mul_f32 v[18:19], v[204:205], v[18:19]
	v_cndmask_b32_e32 v201, 0, v228, vcc
	v_fmac_f32_e32 v201, v200, v140
	v_exp_f32_e32 v201, v201
	v_cndmask_b32_e32 v206, 0, v223, vcc
	v_ldexp_f32 v206, v201, v206
	v_mul_f32_e32 v201, v200, v141
	v_cmp_gt_f32_e32 vcc, s20, v201
	s_nop 1
	v_cndmask_b32_e32 v201, 0, v228, vcc
	v_fmac_f32_e32 v201, v200, v141
	v_exp_f32_e32 v201, v201
	v_cndmask_b32_e32 v207, 0, v223, vcc
	v_ldexp_f32 v207, v201, v207
	v_mul_f32_e32 v201, v200, v142
	v_cmp_gt_f32_e32 vcc, s20, v201
	v_pk_mul_f32 v[4:5], v[206:207], v[4:5]
	v_pk_mul_f32 v[20:21], v[206:207], v[20:21]
	v_cndmask_b32_e32 v201, 0, v228, vcc
	v_fmac_f32_e32 v201, v200, v142
	v_exp_f32_e32 v201, v201
	v_cndmask_b32_e32 v208, 0, v223, vcc
	v_ldexp_f32 v208, v201, v208
	v_mul_f32_e32 v201, v200, v143
	v_cmp_gt_f32_e32 vcc, s20, v201
	s_nop 1
	v_cndmask_b32_e32 v201, 0, v228, vcc
	v_fmac_f32_e32 v201, v200, v143
	v_exp_f32_e32 v201, v201
	v_cndmask_b32_e32 v209, 0, v223, vcc
	v_ldexp_f32 v209, v201, v209
	v_mul_f32_e32 v201, v200, v144
	v_cmp_gt_f32_e32 vcc, s20, v201
	v_pk_mul_f32 v[6:7], v[208:209], v[6:7]
	v_pk_mul_f32 v[22:23], v[208:209], v[22:23]
	v_cndmask_b32_e32 v201, 0, v228, vcc
	v_fmac_f32_e32 v201, v200, v144
	v_exp_f32_e32 v201, v201
	v_cndmask_b32_e32 v234, 0, v223, vcc
	v_ldexp_f32 v234, v201, v234
	v_mul_f32_e32 v201, v200, v145
	v_cmp_gt_f32_e32 vcc, s20, v201
	s_nop 1
	v_cndmask_b32_e32 v201, 0, v228, vcc
	v_fmac_f32_e32 v201, v200, v145
	v_exp_f32_e32 v201, v201
	v_cndmask_b32_e32 v235, 0, v223, vcc
	v_ldexp_f32 v235, v201, v235
	v_mul_f32_e32 v201, v200, v146
	v_cmp_gt_f32_e32 vcc, s20, v201
	v_pk_mul_f32 v[8:9], v[234:235], v[8:9]
	v_pk_mul_f32 v[24:25], v[234:235], v[24:25]
	v_cndmask_b32_e32 v201, 0, v228, vcc
	v_fmac_f32_e32 v201, v200, v146
	v_exp_f32_e32 v201, v201
	v_cndmask_b32_e32 v236, 0, v223, vcc
	v_ldexp_f32 v236, v201, v236
	v_mul_f32_e32 v201, v200, v147
	v_cmp_gt_f32_e32 vcc, s20, v201
	s_nop 1
	v_cndmask_b32_e32 v201, 0, v228, vcc
	v_fmac_f32_e32 v201, v200, v147
	v_exp_f32_e32 v201, v201
	v_cndmask_b32_e32 v237, 0, v223, vcc
	v_ldexp_f32 v237, v201, v237
	v_mul_f32_e32 v201, v200, v148
	v_cmp_gt_f32_e32 vcc, s20, v201
	v_pk_mul_f32 v[10:11], v[236:237], v[10:11]
	v_pk_mul_f32 v[26:27], v[236:237], v[26:27]
	v_cndmask_b32_e32 v201, 0, v228, vcc
	v_fmac_f32_e32 v201, v200, v148
	v_exp_f32_e32 v201, v201
	v_cndmask_b32_e32 v238, 0, v223, vcc
	v_ldexp_f32 v238, v201, v238
	v_mul_f32_e32 v201, v200, v149
	v_cmp_gt_f32_e32 vcc, s20, v201
	s_nop 1
	v_cndmask_b32_e32 v201, 0, v228, vcc
	v_fmac_f32_e32 v201, v200, v149
	v_exp_f32_e32 v201, v201
	v_cndmask_b32_e32 v239, 0, v223, vcc
	v_ldexp_f32 v239, v201, v239
	v_mul_f32_e32 v201, v200, v150
	v_cmp_gt_f32_e32 vcc, s20, v201
	v_pk_mul_f32 v[12:13], v[238:239], v[12:13]
	v_pk_mul_f32 v[28:29], v[238:239], v[28:29]
	v_cndmask_b32_e32 v201, 0, v228, vcc
	v_fmac_f32_e32 v201, v200, v150
	v_exp_f32_e32 v201, v201
	v_cndmask_b32_e32 v240, 0, v223, vcc
	v_ldexp_f32 v240, v201, v240
	v_mul_f32_e32 v201, v200, v151
	v_cmp_gt_f32_e32 vcc, s20, v201
	s_nop 1
	v_cndmask_b32_e32 v201, 0, v228, vcc
	v_fmac_f32_e32 v201, v200, v151
	v_exp_f32_e32 v201, v201
	v_cndmask_b32_e32 v241, 0, v223, vcc
	v_ldexp_f32 v241, v201, v241
	v_pk_mul_f32 v[14:15], v[240:241], v[14:15]
	v_pk_mul_f32 v[30:31], v[240:241], v[30:31]
	s_waitcnt lgkmcnt(1)
	v_mfma_f32_32x32x16_bf16 v[0:15], v[74:77], v[34:37], v[0:15]
	ds_read_b128 v[34:37], v174 offset:34880
	s_waitcnt lgkmcnt(1)
	v_mfma_f32_32x32x16_bf16 v[0:15], v[70:73], v[38:41], v[0:15]
	s_waitcnt lgkmcnt(0)
	v_mfma_f32_32x32x16_bf16 v[0:15], v[66:69], v[34:37], v[0:15]
	ds_read_b128 v[34:37], v174 offset:34912
	s_waitcnt lgkmcnt(0)
	v_mfma_f32_32x32x16_bf16 v[0:15], v[62:65], v[34:37], v[0:15]
	ds_read_b128 v[34:37], v174 offset:34944
	s_waitcnt lgkmcnt(0)
	v_mfma_f32_32x32x16_bf16 v[0:15], v[58:61], v[34:37], v[0:15]
	ds_read_b128 v[34:37], v174 offset:34976
	s_waitcnt lgkmcnt(0)
	v_mfma_f32_32x32x16_bf16 v[0:15], v[54:57], v[34:37], v[0:15]
	ds_read_b128 v[34:37], v174 offset:35008
	s_waitcnt lgkmcnt(0)
	v_mfma_f32_32x32x16_bf16 v[0:15], v[50:53], v[34:37], v[0:15]
	ds_read_b128 v[34:37], v174 offset:35040
	s_waitcnt lgkmcnt(0)
	v_mfma_f32_32x32x16_bf16 v[0:15], v[46:49], v[34:37], v[0:15]
	ds_read_b128 v[34:37], v174 offset:43520
	s_waitcnt lgkmcnt(0)
	v_mfma_f32_32x32x16_bf16 v[16:31], v[74:77], v[34:37], v[16:31]
	ds_read_b128 v[34:37], v174 offset:43552
	s_waitcnt lgkmcnt(0)
	v_mfma_f32_32x32x16_bf16 v[16:31], v[70:73], v[34:37], v[16:31]
	ds_read_b128 v[34:37], v174 offset:43584
	s_waitcnt lgkmcnt(0)
	v_mfma_f32_32x32x16_bf16 v[16:31], v[66:69], v[34:37], v[16:31]
	ds_read_b128 v[34:37], v174 offset:43616
	s_waitcnt lgkmcnt(0)
	v_mfma_f32_32x32x16_bf16 v[16:31], v[62:65], v[34:37], v[16:31]
	ds_read_b128 v[34:37], v174 offset:43648
	s_waitcnt lgkmcnt(0)
	v_mfma_f32_32x32x16_bf16 v[16:31], v[58:61], v[34:37], v[16:31]
	ds_read_b128 v[34:37], v174 offset:43680
	s_waitcnt lgkmcnt(0)
	v_mfma_f32_32x32x16_bf16 v[16:31], v[54:57], v[34:37], v[16:31]
	ds_read_b128 v[34:37], v174 offset:43712
	v_add_u32_e32 v54, s92, v169
	s_waitcnt lgkmcnt(0)
	v_mfma_f32_32x32x16_bf16 v[16:31], v[50:53], v[34:37], v[16:31]
	ds_read_b128 v[34:37], v174 offset:43744
	s_waitcnt lgkmcnt(0)
	v_mfma_f32_32x32x16_bf16 v[16:31], v[46:49], v[34:37], v[16:31]
	v_mul_f32_e32 v34, v200, v152
	v_cmp_gt_f32_e32 vcc, s20, v34
	s_nop 1
	v_cndmask_b32_e32 v34, 0, v228, vcc
	v_fmac_f32_e32 v34, v200, v152
	v_exp_f32_e32 v34, v34
	v_cndmask_b32_e32 v35, 0, v223, vcc
	v_ldexp_f32 v34, v34, v35
	v_mul_f32_e32 v35, v200, v153
	v_cmp_gt_f32_e32 vcc, s20, v35
	s_nop 1
	v_cndmask_b32_e32 v35, 0, v228, vcc
	v_fmac_f32_e32 v35, v200, v153
	v_exp_f32_e32 v35, v35
	v_cndmask_b32_e32 v36, 0, v223, vcc
	v_ldexp_f32 v35, v35, v36
	v_mul_f32_e32 v36, v200, v154
	v_cmp_gt_f32_e32 vcc, s20, v36
	v_pk_mul_f32 v[0:1], v[34:35], v[0:1]
	v_pk_mul_f32 v[16:17], v[34:35], v[16:17]
	v_cndmask_b32_e32 v36, 0, v228, vcc
	v_fmac_f32_e32 v36, v200, v154
	v_exp_f32_e32 v36, v36
	v_cndmask_b32_e32 v37, 0, v223, vcc
	v_ldexp_f32 v36, v36, v37
	v_mul_f32_e32 v37, v200, v155
	v_cmp_gt_f32_e32 vcc, s20, v37
	s_nop 1
	v_cndmask_b32_e32 v37, 0, v228, vcc
	v_fmac_f32_e32 v37, v200, v155
	v_exp_f32_e32 v37, v37
	v_cndmask_b32_e32 v38, 0, v223, vcc
	v_ldexp_f32 v37, v37, v38
	v_mul_f32_e32 v38, v200, v156
	v_cmp_gt_f32_e32 vcc, s20, v38
	v_pk_mul_f32 v[2:3], v[36:37], v[2:3]
	v_pk_mul_f32 v[18:19], v[36:37], v[18:19]
	v_cndmask_b32_e32 v38, 0, v228, vcc
	v_fmac_f32_e32 v38, v200, v156
	v_exp_f32_e32 v38, v38
	v_cndmask_b32_e32 v39, 0, v223, vcc
	v_ldexp_f32 v38, v38, v39
	v_mul_f32_e32 v39, v200, v157
	v_cmp_gt_f32_e32 vcc, s20, v39
	s_nop 1
	v_cndmask_b32_e32 v39, 0, v228, vcc
	v_fmac_f32_e32 v39, v200, v157
	v_exp_f32_e32 v39, v39
	v_cndmask_b32_e32 v40, 0, v223, vcc
	v_ldexp_f32 v39, v39, v40
	v_mul_f32_e32 v40, v200, v158
	v_cmp_gt_f32_e32 vcc, s20, v40
	v_pk_mul_f32 v[4:5], v[38:39], v[4:5]
	v_pk_mul_f32 v[20:21], v[38:39], v[20:21]
	v_cndmask_b32_e32 v40, 0, v228, vcc
	v_fmac_f32_e32 v40, v200, v158
	v_exp_f32_e32 v40, v40
	v_cndmask_b32_e32 v41, 0, v223, vcc
	v_ldexp_f32 v40, v40, v41
	v_mul_f32_e32 v41, v200, v159
	v_cmp_gt_f32_e32 vcc, s20, v41
	s_nop 1
	v_cndmask_b32_e32 v41, 0, v228, vcc
	v_fmac_f32_e32 v41, v200, v159
	v_exp_f32_e32 v41, v41
	v_cndmask_b32_e32 v42, 0, v223, vcc
	v_ldexp_f32 v41, v41, v42
	v_mul_f32_e32 v42, v200, v160
	v_cmp_gt_f32_e32 vcc, s20, v42
	v_pk_mul_f32 v[6:7], v[40:41], v[6:7]
	v_pk_mul_f32 v[22:23], v[40:41], v[22:23]
	v_cndmask_b32_e32 v42, 0, v228, vcc
	v_fmac_f32_e32 v42, v200, v160
	v_exp_f32_e32 v42, v42
	v_cndmask_b32_e32 v43, 0, v223, vcc
	v_ldexp_f32 v42, v42, v43
	v_mul_f32_e32 v43, v200, v161
	v_cmp_gt_f32_e32 vcc, s20, v43
	s_nop 1
	v_cndmask_b32_e32 v43, 0, v228, vcc
	v_fmac_f32_e32 v43, v200, v161
	v_exp_f32_e32 v43, v43
	v_cndmask_b32_e32 v44, 0, v223, vcc
	v_ldexp_f32 v43, v43, v44
	v_mul_f32_e32 v44, v200, v162
	v_cmp_gt_f32_e32 vcc, s20, v44
	v_pk_mul_f32 v[8:9], v[42:43], v[8:9]
	v_pk_mul_f32 v[24:25], v[42:43], v[24:25]
	v_cndmask_b32_e32 v44, 0, v228, vcc
	v_fmac_f32_e32 v44, v200, v162
	v_exp_f32_e32 v44, v44
	v_cndmask_b32_e32 v45, 0, v223, vcc
	v_ldexp_f32 v44, v44, v45
	v_mul_f32_e32 v45, v200, v163
	v_cmp_gt_f32_e32 vcc, s20, v45
	s_nop 1
	v_cndmask_b32_e32 v45, 0, v228, vcc
	v_fmac_f32_e32 v45, v200, v163
	v_exp_f32_e32 v45, v45
	v_cndmask_b32_e32 v46, 0, v223, vcc
	v_ldexp_f32 v45, v45, v46
	v_mul_f32_e32 v46, v200, v164
	v_cmp_gt_f32_e32 vcc, s20, v46
	v_pk_mul_f32 v[10:11], v[44:45], v[10:11]
	v_pk_mul_f32 v[26:27], v[44:45], v[26:27]
	v_cndmask_b32_e32 v46, 0, v228, vcc
	v_fmac_f32_e32 v46, v200, v164
	v_exp_f32_e32 v46, v46
	v_cndmask_b32_e32 v47, 0, v223, vcc
	v_ldexp_f32 v46, v46, v47
	v_mul_f32_e32 v47, v200, v165
	v_cmp_gt_f32_e32 vcc, s20, v47
	s_nop 1
	v_cndmask_b32_e32 v47, 0, v228, vcc
	v_fmac_f32_e32 v47, v200, v165
	v_exp_f32_e32 v47, v47
	v_cndmask_b32_e32 v48, 0, v223, vcc
	v_ldexp_f32 v47, v47, v48
	v_mul_f32_e32 v48, v200, v166
	v_cmp_gt_f32_e32 vcc, s20, v48
	v_pk_mul_f32 v[12:13], v[46:47], v[12:13]
	v_pk_mul_f32 v[28:29], v[46:47], v[28:29]
	v_cndmask_b32_e32 v48, 0, v228, vcc
	v_fmac_f32_e32 v48, v200, v166
	v_exp_f32_e32 v48, v48
	v_cndmask_b32_e32 v49, 0, v223, vcc
	v_ldexp_f32 v48, v48, v49
	v_mul_f32_e32 v49, v200, v167
	v_cmp_gt_f32_e32 vcc, s20, v49
	s_nop 1
	v_cndmask_b32_e32 v49, 0, v228, vcc
	v_fmac_f32_e32 v49, v200, v167
	v_exp_f32_e32 v49, v49
	v_cndmask_b32_e32 v50, 0, v223, vcc
	v_ldexp_f32 v49, v49, v50
	v_pk_mul_f32 v[14:15], v[48:49], v[14:15]
	v_pk_mul_f32 v[30:31], v[48:49], v[30:31]
	ds_read_b64_tr_b16 v[46:47], v168 offset:0
	ds_read_b64_tr_b16 v[48:49], v168 offset:1088
	ds_read_b64_tr_b16 v[42:43], v168 offset:64
	ds_read_b64_tr_b16 v[44:45], v168 offset:1152
	ds_read_b64_tr_b16 v[38:39], v168 offset:4352
	ds_read_b64_tr_b16 v[40:41], v168 offset:5440
	ds_read_b64_tr_b16 v[34:35], v168 offset:4416
	ds_read_b64_tr_b16 v[36:37], v168 offset:5504
	s_waitcnt lgkmcnt(0)
	ds_read_b128 v[50:53], v54
	s_waitcnt lgkmcnt(0)
	v_mfma_f32_32x32x16_bf16 v[0:15], v[50:53], v[46:49], v[0:15]
	v_mfma_f32_32x32x16_bf16 v[16:31], v[50:53], v[42:45], v[16:31]
	v_add_u32_e32 v42, 0, v169
	v_add_u32_e32 v55, 0x11020, v42
	ds_read_b128 v[42:45], v55
	s_waitcnt lgkmcnt(0)
	v_mfma_f32_32x32x16_bf16 v[0:15], v[42:45], v[38:41], v[0:15]
	v_mfma_f32_32x32x16_bf16 v[16:31], v[42:45], v[34:37], v[16:31]
	ds_read_b64_tr_b16 v[46:47], v170 offset:0
	ds_read_b64_tr_b16 v[48:49], v170 offset:1088
	ds_read_b64_tr_b16 v[42:43], v170 offset:64
	ds_read_b64_tr_b16 v[44:45], v170 offset:1152
	ds_read_b64_tr_b16 v[38:39], v170 offset:4352
	ds_read_b64_tr_b16 v[40:41], v170 offset:5440
	ds_read_b64_tr_b16 v[34:35], v170 offset:4416
	ds_read_b64_tr_b16 v[36:37], v170 offset:5504
	s_waitcnt lgkmcnt(0)
	ds_read_b128 v[50:53], v54 offset:64
	s_waitcnt lgkmcnt(0)
	v_mfma_f32_32x32x16_bf16 v[16:31], v[50:53], v[42:45], v[16:31]
	ds_read_b128 v[42:45], v55 offset:64
	v_mfma_f32_32x32x16_bf16 v[0:15], v[50:53], v[46:49], v[0:15]
	s_waitcnt lgkmcnt(0)
	v_mfma_f32_32x32x16_bf16 v[0:15], v[42:45], v[38:41], v[0:15]
	v_mfma_f32_32x32x16_bf16 v[16:31], v[42:45], v[34:37], v[16:31]
	ds_read_b64_tr_b16 v[46:47], v171 offset:0
	ds_read_b64_tr_b16 v[48:49], v171 offset:1088
	ds_read_b64_tr_b16 v[42:43], v171 offset:64
	ds_read_b64_tr_b16 v[44:45], v171 offset:1152
	ds_read_b64_tr_b16 v[38:39], v171 offset:4352
	ds_read_b64_tr_b16 v[40:41], v171 offset:5440
	ds_read_b64_tr_b16 v[34:35], v171 offset:4416
	ds_read_b64_tr_b16 v[36:37], v171 offset:5504
	s_waitcnt lgkmcnt(0)
	ds_read_b128 v[50:53], v54 offset:128
	s_waitcnt lgkmcnt(0)
	v_mfma_f32_32x32x16_bf16 v[16:31], v[50:53], v[42:45], v[16:31]
	ds_read_b128 v[42:45], v55 offset:128
	v_mfma_f32_32x32x16_bf16 v[0:15], v[50:53], v[46:49], v[0:15]
	s_waitcnt lgkmcnt(0)
	v_mfma_f32_32x32x16_bf16 v[0:15], v[42:45], v[38:41], v[0:15]
	v_mfma_f32_32x32x16_bf16 v[16:31], v[42:45], v[34:37], v[16:31]
	ds_read_b64_tr_b16 v[46:47], v172 offset:0
	ds_read_b64_tr_b16 v[48:49], v172 offset:1088
	ds_read_b64_tr_b16 v[42:43], v172 offset:64
	ds_read_b64_tr_b16 v[44:45], v172 offset:1152
	ds_read_b64_tr_b16 v[38:39], v172 offset:4352
	ds_read_b64_tr_b16 v[40:41], v172 offset:5440
	ds_read_b64_tr_b16 v[34:35], v172 offset:4416
	ds_read_b64_tr_b16 v[36:37], v172 offset:5504
	s_waitcnt lgkmcnt(0)
	ds_read_b128 v[50:53], v54 offset:192
	s_waitcnt lgkmcnt(0)
	v_mfma_f32_32x32x16_bf16 v[16:31], v[50:53], v[42:45], v[16:31]
	ds_read_b128 v[42:45], v55 offset:192
	s_waitcnt lgkmcnt(0)
	s_barrier
	v_mfma_f32_32x32x16_bf16 v[0:15], v[50:53], v[46:49], v[0:15]
	v_mfma_f32_32x32x16_bf16 v[0:15], v[42:45], v[38:41], v[0:15]
	v_mfma_f32_32x32x16_bf16 v[16:31], v[42:45], v[34:37], v[16:31]
	s_nop 11
	ds_write2_b32 v175, v0, v16 offset1:32
	ds_write2_b32 v175, v1, v17 offset0:132 offset1:164
	v_add_u32_e32 v0, 0x400, v175
	ds_write2_b32 v0, v2, v18 offset0:8 offset1:40
	ds_write2_b32 v0, v3, v19 offset0:140 offset1:172
	v_add_u32_e32 v0, 0x1000, v175
	ds_write2_b32 v0, v4, v20 offset0:32 offset1:64
	ds_write2_b32 v0, v5, v21 offset0:164 offset1:196
	v_add_u32_e32 v0, 0x1400, v175
	ds_write2_b32 v0, v6, v22 offset0:40 offset1:72
	ds_write2_b32 v0, v7, v23 offset0:172 offset1:204
	v_add_u32_e32 v0, 0x2000, v175
	ds_write2_b32 v0, v8, v24 offset0:64 offset1:96
	ds_write2_b32 v0, v9, v25 offset0:196 offset1:228
	v_add_u32_e32 v0, 0x2400, v175
	ds_write2_b32 v0, v10, v26 offset0:72 offset1:104
	ds_write2_b32 v0, v11, v27 offset0:204 offset1:236
	v_add_u32_e32 v0, 0x3000, v175
	ds_write2_b32 v0, v12, v28 offset0:96 offset1:128
	v_add_u32_e32 v0, 0x3200, v175
	ds_write2_b32 v0, v13, v29 offset0:100 offset1:132
	v_add_u32_e32 v0, 0x3400, v175
	ds_write2_b32 v0, v14, v30 offset0:104 offset1:136
	v_add_u32_e32 v0, 0x3600, v175
	ds_write2_b32 v0, v15, v31 offset0:108 offset1:140
	v_lshl_add_u64 v[0:1], v[88:89], 0, s[8:9]
	v_lshl_add_u64 v[24:25], s[0:1], 0, v[90:91]
	s_waitcnt lgkmcnt(0)
	s_barrier
	global_load_dwordx4 v[12:15], v[0:1], off offset:16
	global_load_dwordx4 v[16:19], v[0:1], off
	v_mad_u64_u32 v[0:1], s[0:1], v24, s97, v[98:99]
	v_mov_b32_e32 v2, v1
	v_mad_u64_u32 v[2:3], s[0:1], v25, s97, v[2:3]
	v_mov_b32_e32 v1, v2
	v_lshl_add_u64 v[0:1], v[0:1], 0, s[88:89]
	v_lshl_add_u64 v[20:21], v[0:1], 0, v[32:33]
	v_add_co_u32_e32 v0, vcc, s96, v20
	s_mov_b32 s0, 0xd000
	s_nop 0
	v_addc_co_u32_e32 v1, vcc, 0, v21, vcc
	v_add_co_u32_e32 v4, vcc, s0, v20
	s_mov_b32 s0, 0x18000
	s_nop 0
	v_addc_co_u32_e32 v5, vcc, 0, v21, vcc
	v_add_co_u32_e32 v8, vcc, s0, v20
	s_mov_b32 s0, 0x23000
	s_nop 0
	v_addc_co_u32_e32 v9, vcc, 0, v21, vcc
	v_add_co_u32_e32 v20, vcc, s0, v20
	global_load_dwordx4 v[0:3], v[0:1], off offset:2048
	s_nop 0
	v_addc_co_u32_e32 v21, vcc, 0, v21, vcc
	global_load_dwordx4 v[4:7], v[4:5], off offset:2048
	s_nop 0
	global_load_dwordx4 v[8:11], v[8:9], off offset:2048
	s_nop 0
	global_load_dwordx4 v[20:23], v[20:21], off offset:2048
	ds_read_b128 v[46:49], v176
	ds_read_b128 v[50:53], v176 offset:16
	ds_read_b128 v[54:57], v176 offset:2112
	ds_read_b128 v[58:61], v176 offset:2128
	ds_read_b128 v[62:65], v176 offset:4224
	ds_read_b128 v[66:69], v176 offset:4240
	ds_read_b128 v[70:73], v176 offset:6336
	ds_read_b128 v[74:77], v176 offset:6352
	s_waitcnt lgkmcnt(6)
	v_add_f32_e32 v34, 0, v46
	v_add_f32_e32 v34, v47, v34
	v_add_f32_e32 v34, v48, v34
	v_add_f32_e32 v34, v49, v34
	v_add_f32_e32 v34, v50, v34
	v_add_f32_e32 v34, v51, v34
	v_add_f32_e32 v34, v52, v34
	v_add_f32_e32 v34, v53, v34
	s_waitcnt lgkmcnt(4)
	v_add_f32_e32 v35, 0, v54
	v_add_f32_e32 v35, v55, v35
	v_add_f32_e32 v35, v56, v35
	v_add_f32_e32 v35, v57, v35
	v_add_f32_e32 v35, v58, v35
	v_add_f32_e32 v35, v59, v35
	v_add_f32_e32 v35, v60, v35
	v_add_f32_e32 v35, v61, v35
	s_waitcnt lgkmcnt(2)
	v_add_f32_e32 v36, 0, v62
	v_add_f32_e32 v36, v63, v36
	v_add_f32_e32 v36, v64, v36
	v_add_f32_e32 v36, v65, v36
	v_add_f32_e32 v36, v66, v36
	v_add_f32_e32 v36, v67, v36
	v_add_f32_e32 v36, v68, v36
	v_add_f32_e32 v36, v69, v36
	s_waitcnt lgkmcnt(0)
	v_add_f32_e32 v37, 0, v70
	v_add_f32_e32 v37, v71, v37
	v_add_f32_e32 v37, v72, v37
	v_add_f32_e32 v37, v73, v37
	v_add_f32_e32 v37, v74, v37
	v_add_f32_e32 v37, v75, v37
	v_add_f32_e32 v37, v76, v37
	v_add_f32_e32 v37, v77, v37
	ds_bpermute_b32 v38, v233, v34
	ds_bpermute_b32 v39, v233, v35
	ds_bpermute_b32 v40, v233, v36
	ds_bpermute_b32 v78, v233, v37
	s_waitcnt lgkmcnt(3)
	v_add_f32_e32 v34, v34, v38
	s_waitcnt lgkmcnt(2)
	v_add_f32_e32 v35, v35, v39
	s_waitcnt lgkmcnt(1)
	v_add_f32_e32 v36, v36, v40
	s_waitcnt lgkmcnt(0)
	v_add_f32_e32 v37, v37, v78
	ds_bpermute_b32 v38, v232, v34
	ds_bpermute_b32 v39, v232, v35
	ds_bpermute_b32 v40, v232, v36
	ds_bpermute_b32 v78, v232, v37
	s_waitcnt lgkmcnt(3)
	v_add_f32_e32 v34, v34, v38
	s_waitcnt lgkmcnt(2)
	v_add_f32_e32 v35, v35, v39
	s_waitcnt lgkmcnt(1)
	v_add_f32_e32 v36, v36, v40
	s_waitcnt lgkmcnt(0)
	v_add_f32_e32 v37, v37, v78
	ds_bpermute_b32 v38, v231, v34
	ds_bpermute_b32 v39, v231, v35
	ds_bpermute_b32 v40, v231, v36
	ds_bpermute_b32 v78, v231, v37
	s_waitcnt lgkmcnt(3)
	v_add_f32_e32 v34, v34, v38
	s_waitcnt lgkmcnt(2)
	v_add_f32_e32 v35, v35, v39
	s_waitcnt lgkmcnt(1)
	v_add_f32_e32 v36, v36, v40
	s_waitcnt lgkmcnt(0)
	v_add_f32_e32 v37, v37, v78
	ds_bpermute_b32 v38, v230, v34
	ds_bpermute_b32 v39, v230, v35
	ds_bpermute_b32 v40, v230, v36
	ds_bpermute_b32 v78, v230, v37
	s_waitcnt lgkmcnt(3)
	v_add_f32_e32 v34, v34, v38
	s_waitcnt lgkmcnt(2)
	v_add_f32_e32 v35, v35, v39
	s_waitcnt lgkmcnt(1)
	v_add_f32_e32 v36, v36, v40
	s_waitcnt lgkmcnt(0)
	v_add_f32_e32 v37, v37, v78
	v_mul_f32_e32 v38, 0x3c000000, v34
	v_mul_f32_e32 v39, 0x3c000000, v35
	v_mul_f32_e32 v40, 0x3c000000, v36
	v_mul_f32_e32 v78, 0x3c000000, v37
	v_sub_f32_e32 v46, v46, v38
	v_sub_f32_e32 v47, v47, v38
	v_sub_f32_e32 v48, v48, v38
	v_sub_f32_e32 v49, v49, v38
	v_sub_f32_e32 v50, v50, v38
	v_sub_f32_e32 v51, v51, v38
	v_sub_f32_e32 v52, v52, v38
	v_sub_f32_e32 v53, v53, v38
	v_sub_f32_e32 v54, v54, v39
	v_sub_f32_e32 v55, v55, v39
	v_sub_f32_e32 v56, v56, v39
	v_sub_f32_e32 v57, v57, v39
	v_sub_f32_e32 v58, v58, v39
	v_sub_f32_e32 v59, v59, v39
	v_sub_f32_e32 v60, v60, v39
	v_sub_f32_e32 v61, v61, v39
	v_sub_f32_e32 v62, v62, v40
	v_sub_f32_e32 v63, v63, v40
	v_sub_f32_e32 v64, v64, v40
	v_sub_f32_e32 v65, v65, v40
	v_sub_f32_e32 v66, v66, v40
	v_sub_f32_e32 v67, v67, v40
	v_sub_f32_e32 v68, v68, v40
	v_sub_f32_e32 v69, v69, v40
	v_sub_f32_e32 v70, v70, v78
	v_sub_f32_e32 v71, v71, v78
	v_sub_f32_e32 v72, v72, v78
	v_sub_f32_e32 v73, v73, v78
	v_sub_f32_e32 v74, v74, v78
	v_sub_f32_e32 v75, v75, v78
	v_sub_f32_e32 v76, v76, v78
	v_sub_f32_e32 v77, v77, v78
	v_mul_f32_e32 v34, v47, v47
	v_fmac_f32_e32 v34, v46, v46
	v_mul_f32_e32 v35, v55, v55
	v_fmac_f32_e32 v35, v54, v54
	v_mul_f32_e32 v36, v63, v63
	v_fmac_f32_e32 v36, v62, v62
	v_mul_f32_e32 v37, v71, v71
	v_fmac_f32_e32 v37, v70, v70
	v_mul_f32_e32 v38, v48, v48
	v_mul_f32_e32 v39, v56, v56
	v_mul_f32_e32 v40, v64, v64
	v_mul_f32_e32 v78, v72, v72
	v_add_f32_e32 v34, v38, v34
	v_add_f32_e32 v35, v39, v35
	v_add_f32_e32 v36, v40, v36
	v_add_f32_e32 v37, v78, v37
	v_mul_f32_e32 v38, v49, v49
	v_mul_f32_e32 v39, v57, v57
	v_mul_f32_e32 v40, v65, v65
	v_mul_f32_e32 v78, v73, v73
	v_add_f32_e32 v34, v38, v34
	v_add_f32_e32 v35, v39, v35
	v_add_f32_e32 v36, v40, v36
	v_add_f32_e32 v37, v78, v37
	v_mul_f32_e32 v38, v50, v50
	v_mul_f32_e32 v39, v58, v58
	v_mul_f32_e32 v40, v66, v66
	v_mul_f32_e32 v78, v74, v74
	v_add_f32_e32 v34, v38, v34
	v_add_f32_e32 v35, v39, v35
	v_add_f32_e32 v36, v40, v36
	v_add_f32_e32 v37, v78, v37
	v_mul_f32_e32 v38, v51, v51
	v_mul_f32_e32 v39, v59, v59
	v_mul_f32_e32 v40, v67, v67
	v_mul_f32_e32 v78, v75, v75
	v_add_f32_e32 v34, v38, v34
	v_add_f32_e32 v35, v39, v35
	v_add_f32_e32 v36, v40, v36
	v_add_f32_e32 v37, v78, v37
	v_mul_f32_e32 v38, v52, v52
	v_mul_f32_e32 v39, v60, v60
	v_mul_f32_e32 v40, v68, v68
	v_mul_f32_e32 v78, v76, v76
	v_add_f32_e32 v34, v38, v34
	v_add_f32_e32 v35, v39, v35
	v_add_f32_e32 v36, v40, v36
	v_add_f32_e32 v37, v78, v37
	v_mul_f32_e32 v38, v53, v53
	v_mul_f32_e32 v39, v61, v61
	v_mul_f32_e32 v40, v69, v69
	v_mul_f32_e32 v78, v77, v77
	v_add_f32_e32 v34, v38, v34
	v_add_f32_e32 v35, v39, v35
	v_add_f32_e32 v36, v40, v36
	v_add_f32_e32 v37, v78, v37
	ds_bpermute_b32 v38, v233, v34
	ds_bpermute_b32 v39, v233, v35
	ds_bpermute_b32 v40, v233, v36
	ds_bpermute_b32 v78, v233, v37
	s_waitcnt lgkmcnt(3)
	v_add_f32_e32 v34, v34, v38
	s_waitcnt lgkmcnt(2)
	v_add_f32_e32 v35, v35, v39
	s_waitcnt lgkmcnt(1)
	v_add_f32_e32 v36, v36, v40
	s_waitcnt lgkmcnt(0)
	v_add_f32_e32 v37, v37, v78
	ds_bpermute_b32 v38, v232, v34
	ds_bpermute_b32 v39, v232, v35
	ds_bpermute_b32 v40, v232, v36
	ds_bpermute_b32 v78, v232, v37
	s_waitcnt lgkmcnt(3)
	v_add_f32_e32 v34, v34, v38
	s_waitcnt lgkmcnt(2)
	v_add_f32_e32 v35, v35, v39
	s_waitcnt lgkmcnt(1)
	v_add_f32_e32 v36, v36, v40
	s_waitcnt lgkmcnt(0)
	v_add_f32_e32 v37, v37, v78
	ds_bpermute_b32 v38, v231, v34
	ds_bpermute_b32 v39, v231, v35
	ds_bpermute_b32 v40, v231, v36
	ds_bpermute_b32 v78, v231, v37
	s_waitcnt lgkmcnt(3)
	v_add_f32_e32 v34, v34, v38
	s_waitcnt lgkmcnt(2)
	v_add_f32_e32 v35, v35, v39
	s_waitcnt lgkmcnt(1)
	v_add_f32_e32 v36, v36, v40
	s_waitcnt lgkmcnt(0)
	v_add_f32_e32 v37, v37, v78
	ds_bpermute_b32 v38, v230, v34
	ds_bpermute_b32 v39, v230, v35
	ds_bpermute_b32 v40, v230, v36
	ds_bpermute_b32 v78, v230, v37
	s_waitcnt lgkmcnt(3)
	v_add_f32_e32 v34, v34, v38
	s_waitcnt lgkmcnt(2)
	v_add_f32_e32 v35, v35, v39
	s_waitcnt lgkmcnt(1)
	v_add_f32_e32 v36, v36, v40
	s_waitcnt lgkmcnt(0)
	v_add_f32_e32 v37, v37, v78
	v_fmamk_f32 v34, v34, 0x3c000000, v218
	v_cmp_gt_f32_e32 vcc, s18, v34
	v_mul_f32_e32 v38, 0x4b800000, v34
	s_nop 0
	v_cndmask_b32_e32 v34, v34, v38, vcc
	v_rsq_f32_e32 v34, v34
	s_nop 0
	v_mul_f32_e32 v38, 0x45800000, v34
	v_cndmask_b32_e32 v34, v34, v38, vcc
	v_fmamk_f32 v35, v35, 0x3c000000, v218
	v_cmp_gt_f32_e32 vcc, s18, v35
	v_mul_f32_e32 v39, 0x4b800000, v35
	s_nop 0
	v_cndmask_b32_e32 v35, v35, v39, vcc
	v_rsq_f32_e32 v35, v35
	s_nop 0
	v_mul_f32_e32 v39, 0x45800000, v35
	v_cndmask_b32_e32 v35, v35, v39, vcc
	v_fmamk_f32 v36, v36, 0x3c000000, v218
	v_cmp_gt_f32_e32 vcc, s18, v36
	v_mul_f32_e32 v40, 0x4b800000, v36
	s_nop 0
	v_cndmask_b32_e32 v36, v36, v40, vcc
	v_rsq_f32_e32 v36, v36
	s_nop 0
	v_mul_f32_e32 v40, 0x45800000, v36
	v_cndmask_b32_e32 v36, v36, v40, vcc
	v_fmamk_f32 v37, v37, 0x3c000000, v218
	v_cmp_gt_f32_e32 vcc, s18, v37
	v_mul_f32_e32 v78, 0x4b800000, v37
	s_nop 0
	v_cndmask_b32_e32 v37, v37, v78, vcc
	v_rsq_f32_e32 v37, v37
	s_nop 0
	v_mul_f32_e32 v78, 0x45800000, v37
	v_cndmask_b32_e32 v37, v37, v78, vcc
	s_waitcnt vmcnt(0)
	v_mul_f32_e32 v46, v46, v34
	v_mul_f32_e32 v46, v16, v46
	v_mul_f32_e32 v47, v47, v34
	v_mul_f32_e32 v47, v17, v47
	v_mul_f32_e32 v48, v48, v34
	v_mul_f32_e32 v48, v18, v48
	v_mul_f32_e32 v49, v49, v34
	v_mul_f32_e32 v49, v19, v49
	v_mul_f32_e32 v50, v50, v34
	v_mul_f32_e32 v50, v12, v50
	v_mul_f32_e32 v51, v51, v34
	v_mul_f32_e32 v51, v13, v51
	v_mul_f32_e32 v52, v52, v34
	v_mul_f32_e32 v52, v14, v52
	v_mul_f32_e32 v53, v53, v34
	v_mul_f32_e32 v53, v15, v53
	v_lshlrev_b32_e32 v79, 16, v0
	v_and_b32_e32 v80, 0xffff0000, v0
	v_mul_f32_e32 v79, v46, v79
	v_mul_f32_e32 v80, v47, v80
	v_cvt_pk_bf16_f32 v0, v79, v80
	v_lshlrev_b32_e32 v79, 16, v1
	v_and_b32_e32 v80, 0xffff0000, v1
	v_mul_f32_e32 v79, v48, v79
	v_mul_f32_e32 v80, v49, v80
	v_cvt_pk_bf16_f32 v1, v79, v80
	v_lshlrev_b32_e32 v79, 16, v2
	v_and_b32_e32 v80, 0xffff0000, v2
	v_mul_f32_e32 v79, v50, v79
	v_mul_f32_e32 v80, v51, v80
	v_cvt_pk_bf16_f32 v2, v79, v80
	v_lshlrev_b32_e32 v79, 16, v3
	v_and_b32_e32 v80, 0xffff0000, v3
	v_mul_f32_e32 v79, v52, v79
	v_mul_f32_e32 v80, v53, v80
	v_cvt_pk_bf16_f32 v3, v79, v80
	v_mul_f32_e32 v54, v54, v35
	v_mul_f32_e32 v54, v16, v54
	v_mul_f32_e32 v55, v55, v35
	v_mul_f32_e32 v55, v17, v55
	v_mul_f32_e32 v56, v56, v35
	v_mul_f32_e32 v56, v18, v56
	v_mul_f32_e32 v57, v57, v35
	v_mul_f32_e32 v57, v19, v57
	v_mul_f32_e32 v58, v58, v35
	v_mul_f32_e32 v58, v12, v58
	v_mul_f32_e32 v59, v59, v35
	v_mul_f32_e32 v59, v13, v59
	v_mul_f32_e32 v60, v60, v35
	v_mul_f32_e32 v60, v14, v60
	v_mul_f32_e32 v61, v61, v35
	v_mul_f32_e32 v61, v15, v61
	v_lshlrev_b32_e32 v79, 16, v4
	v_and_b32_e32 v80, 0xffff0000, v4
	v_mul_f32_e32 v79, v54, v79
	v_mul_f32_e32 v80, v55, v80
	v_cvt_pk_bf16_f32 v4, v79, v80
	v_lshlrev_b32_e32 v79, 16, v5
	v_and_b32_e32 v80, 0xffff0000, v5
	v_mul_f32_e32 v79, v56, v79
	v_mul_f32_e32 v80, v57, v80
	v_cvt_pk_bf16_f32 v5, v79, v80
	v_lshlrev_b32_e32 v79, 16, v6
	v_and_b32_e32 v80, 0xffff0000, v6
	v_mul_f32_e32 v79, v58, v79
	v_mul_f32_e32 v80, v59, v80
	v_cvt_pk_bf16_f32 v6, v79, v80
	v_lshlrev_b32_e32 v79, 16, v7
	v_and_b32_e32 v80, 0xffff0000, v7
	v_mul_f32_e32 v79, v60, v79
	v_mul_f32_e32 v80, v61, v80
	v_cvt_pk_bf16_f32 v7, v79, v80
	v_mul_f32_e32 v62, v62, v36
	v_mul_f32_e32 v62, v16, v62
	v_mul_f32_e32 v63, v63, v36
	v_mul_f32_e32 v63, v17, v63
	v_mul_f32_e32 v64, v64, v36
	v_mul_f32_e32 v64, v18, v64
	v_mul_f32_e32 v65, v65, v36
	v_mul_f32_e32 v65, v19, v65
	v_mul_f32_e32 v66, v66, v36
	v_mul_f32_e32 v66, v12, v66
	v_mul_f32_e32 v67, v67, v36
	v_mul_f32_e32 v67, v13, v67
	v_mul_f32_e32 v68, v68, v36
	v_mul_f32_e32 v68, v14, v68
	v_mul_f32_e32 v69, v69, v36
	v_mul_f32_e32 v69, v15, v69
	v_lshlrev_b32_e32 v79, 16, v8
	v_and_b32_e32 v80, 0xffff0000, v8
	v_mul_f32_e32 v79, v62, v79
	v_mul_f32_e32 v80, v63, v80
	v_cvt_pk_bf16_f32 v8, v79, v80
	v_lshlrev_b32_e32 v79, 16, v9
	v_and_b32_e32 v80, 0xffff0000, v9
	v_mul_f32_e32 v79, v64, v79
	v_mul_f32_e32 v80, v65, v80
	v_cvt_pk_bf16_f32 v9, v79, v80
	v_lshlrev_b32_e32 v79, 16, v10
	v_and_b32_e32 v80, 0xffff0000, v10
	v_mul_f32_e32 v79, v66, v79
	v_mul_f32_e32 v80, v67, v80
	v_cvt_pk_bf16_f32 v10, v79, v80
	v_lshlrev_b32_e32 v79, 16, v11
	v_and_b32_e32 v80, 0xffff0000, v11
	v_mul_f32_e32 v79, v68, v79
	v_mul_f32_e32 v80, v69, v80
	v_cvt_pk_bf16_f32 v11, v79, v80
	v_mul_f32_e32 v70, v70, v37
	v_mul_f32_e32 v70, v16, v70
	v_mul_f32_e32 v71, v71, v37
	v_mul_f32_e32 v71, v17, v71
	v_mul_f32_e32 v72, v72, v37
	v_mul_f32_e32 v72, v18, v72
	v_mul_f32_e32 v73, v73, v37
	v_mul_f32_e32 v73, v19, v73
	v_mul_f32_e32 v74, v74, v37
	v_mul_f32_e32 v74, v12, v74
	v_mul_f32_e32 v75, v75, v37
	v_mul_f32_e32 v75, v13, v75
	v_mul_f32_e32 v76, v76, v37
	v_mul_f32_e32 v76, v14, v76
	v_mul_f32_e32 v77, v77, v37
	v_mul_f32_e32 v77, v15, v77
	v_lshlrev_b32_e32 v79, 16, v20
	v_and_b32_e32 v80, 0xffff0000, v20
	v_mul_f32_e32 v79, v70, v79
	v_mul_f32_e32 v80, v71, v80
	v_cvt_pk_bf16_f32 v20, v79, v80
	v_lshlrev_b32_e32 v79, 16, v21
	v_and_b32_e32 v80, 0xffff0000, v21
	v_mul_f32_e32 v79, v72, v79
	v_mul_f32_e32 v80, v73, v80
	v_cvt_pk_bf16_f32 v21, v79, v80
	v_lshlrev_b32_e32 v79, 16, v22
	v_and_b32_e32 v80, 0xffff0000, v22
	v_mul_f32_e32 v79, v74, v79
	v_mul_f32_e32 v80, v75, v80
	v_cvt_pk_bf16_f32 v22, v79, v80
	v_lshlrev_b32_e32 v79, 16, v23
	v_and_b32_e32 v80, 0xffff0000, v23
	v_mul_f32_e32 v79, v76, v79
	v_mul_f32_e32 v80, v77, v80
	v_cvt_pk_bf16_f32 v23, v79, v80
	v_lshlrev_b64 v[26:27], 12, v[24:25]
	v_mov_b32_e32 v28, v26
	v_mov_b32_e32 v29, v27
	v_lshl_add_u64 v[28:29], s[4:5], 0, v[28:29]
	v_lshl_add_u64 v[28:29], v[28:29], 0, s[88:89]
	v_lshl_add_u64 v[28:29], v[28:29], 0, v[32:33]
	v_add_co_u32_e32 v28, vcc, s24, v28
	s_nop 1
	v_addc_co_u32_e32 v29, vcc, 0, v29, vcc
	global_store_dwordx4 v[28:29], v[0:3], off offset:3072
	v_or_b32_e32 v28, 0x4000, v26
	v_mov_b32_e32 v29, v27
	v_lshl_add_u64 v[28:29], s[4:5], 0, v[28:29]
	v_lshl_add_u64 v[28:29], v[28:29], 0, s[88:89]
	v_lshl_add_u64 v[28:29], v[28:29], 0, v[32:33]
	v_add_co_u32_e32 v28, vcc, s24, v28
	s_nop 1
	v_addc_co_u32_e32 v29, vcc, 0, v29, vcc
	global_store_dwordx4 v[28:29], v[4:7], off offset:3072
	v_or_b32_e32 v28, 0x8000, v26
	v_mov_b32_e32 v29, v27
	v_lshl_add_u64 v[28:29], s[4:5], 0, v[28:29]
	v_lshl_add_u64 v[28:29], v[28:29], 0, s[88:89]
	v_lshl_add_u64 v[28:29], v[28:29], 0, v[32:33]
	v_add_co_u32_e32 v28, vcc, s24, v28
	s_nop 1
	v_addc_co_u32_e32 v29, vcc, 0, v29, vcc
	global_store_dwordx4 v[28:29], v[8:11], off offset:3072
	v_or_b32_e32 v28, 0xc000, v26
	v_mov_b32_e32 v29, v27
	v_lshl_add_u64 v[28:29], s[4:5], 0, v[28:29]
	v_lshl_add_u64 v[28:29], v[28:29], 0, s[88:89]
	v_lshl_add_u64 v[28:29], v[28:29], 0, v[32:33]
	v_add_co_u32_e32 v28, vcc, s24, v28
	s_nop 1
	v_addc_co_u32_e32 v29, vcc, 0, v29, vcc
	global_store_dwordx4 v[28:29], v[20:23], off offset:3072
	s_cbranch_scc1 .LBB0_802
